# P2: C/B softmax-offset preambles hoisted to P2 start (one load round trip instead of three), values parked in SGPRs
# baseline (speedup 1.0000x reference)
; #define LAS __attribute__((address_space(3)))
; #define UNIFORM_F(v) __builtin_bit_cast(float, __builtin_amdgcn_readfirstlane(__builtin_bit_cast(int, (float)(v))))
; __device__ __forceinline__ float wave_sum(float v) {
;     v += pg8::shx<1>(v); v += pg8::shx<2>(v); v += pg8::shx<4>(v); v += pg8::shx<8>(v); v += pg8::shx<16>(v); v = pg8::sum_halves(v);
;     return v;
; }
; __device__ __forceinline__ float wave_max(float v) {
;     v = fmaxf(v, pg8::shx<1>(v)); v = fmaxf(v, pg8::shx<2>(v)); v = fmaxf(v, pg8::shx<4>(v)); v = fmaxf(v, pg8::shx<8>(v)); v = fmaxf(v, pg8::shx<16>(v)); v = pg8::max_halves(v);
;     return v;
; }
; __device__ __forceinline__ float absmax_vec(const float* g, int n, int lane) {
;     float v = fabsf(g[lane]); if (n > 64) v = fmaxf(v, fabsf(g[lane + 64]));
;     return wave_max(v);
; }
; __global__ void __launch_bounds__(512, 2) fwd_megakernel(Args a) {
;     ...
;         const float negM_a = UNIFORM_F(-8.f * absmax_vec(a.in[6], 64, lane) * absmax_vec(a.in[7], 64, lane) * L2E);
;         const float lam = UNIFORM_F(expf(wave_sum(a.in[8][lane] * a.in[9][lane])) - expf(wave_sum(a.in[10][lane] * a.in[11][lane])) + 0.2f);
;         *(LAS float*)(lds + (LDS_BYTES - 64 + 32)) = lam;
.LBB0_259:
	v_writelane_b32 v255, s81, 2
	v_writelane_b32 v255, s79, 3
	v_writelane_b32 v255, s78, 4
	s_or_b64 exec, exec, s[4:5]
	s_mov_b32 s4, 0
	s_waitcnt lgkmcnt(0)
	s_barrier
	s_load_dwordx2 s[98:99], s[0:1], 0x88
	s_load_dwordx2 s[100:101], s[0:1], 0x90
	s_load_dwordx4 s[20:23], s[0:1], 0x50
	v_mbcnt_lo_u32_b32 v0, -1, s4
	s_load_dwordx8 s[4:11], s[0:1], 0x30
	v_mbcnt_hi_u32_b32 v0, -1, v0
	v_ashrrev_i32_e32 v1, 31, v0
	v_lshlrev_b64 v[0:1], 2, v[0:1]
	s_abs_i32 s30, s24
	s_waitcnt lgkmcnt(0)
	v_mov_b32_e32 v248, v0
	global_load_dword v240, v248, s[98:99]
	global_load_dword v241, v248, s[98:99] offset:256
	global_load_dword v242, v248, s[100:101] offset:256
	global_load_dword v243, v248, s[100:101]
	s_load_dwordx2 s[98:99], s[0:1], 0x68
	s_load_dwordx2 s[100:101], s[0:1], 0x70
	s_waitcnt lgkmcnt(0)
	global_load_dword v244, v248, s[98:99]
	global_load_dword v245, v248, s[98:99] offset:256
	global_load_dword v246, v248, s[100:101] offset:256
	global_load_dword v247, v248, s[100:101]
	v_lshl_add_u64 v[2:3], s[4:5], 0, v[0:1]
	global_load_dword v4, v[2:3], off
	v_lshl_add_u64 v[2:3], s[6:7], 0, v[0:1]
	global_load_dword v5, v[2:3], off
	v_lshl_add_u64 v[2:3], s[8:9], 0, v[0:1]
	global_load_dword v6, v[2:3], off
	v_lshl_add_u64 v[2:3], s[10:11], 0, v[0:1]
	global_load_dword v7, v[2:3], off
	v_lshl_add_u64 v[2:3], s[20:21], 0, v[0:1]
	v_lshl_add_u64 v[0:1], s[22:23], 0, v[0:1]
	global_load_dword v2, v[2:3], off
	s_mov_b32 s4, 0x3fb8aa3b
	global_load_dword v0, v[0:1], off
	s_mov_b32 s5, 0xc2ce8ed0
	s_mov_b32 s6, 0x42b17218
	s_sub_i32 s8, 0, s30
	s_ashr_i32 s81, s24, 31
	s_add_i32 s33, 0, 0x25fe0
	s_mov_b32 s7, 0
	s_waitcnt vmcnt(5)
	v_and_b32_e32 v1, 0x7fffffff, v4
	v_max_f32_e64 v3, |v4|, |v4|
	s_waitcnt vmcnt(4)
	v_and_b32_e32 v4, 0x7fffffff, v5
	ds_swizzle_b32 v1, v1 offset:swizzle(SWAP,1)
	ds_swizzle_b32 v4, v4 offset:swizzle(SWAP,1)
	v_max_f32_e64 v5, |v5|, |v5|
	s_waitcnt vmcnt(2)
	v_mul_f32_e32 v8, v6, v7
	ds_swizzle_b32 v8, v8 offset:swizzle(SWAP,1)
	s_waitcnt lgkmcnt(2)
	v_max_f32_e32 v1, v1, v1
	s_waitcnt lgkmcnt(1)
	v_max_f32_e32 v4, v4, v4
	s_waitcnt vmcnt(0)
	v_mul_f32_e32 v9, v2, v0
	ds_swizzle_b32 v9, v9 offset:swizzle(SWAP,1)
	s_waitcnt lgkmcnt(1)
	v_fmac_f32_e32 v8, v6, v7
	v_mov_b32_e32 v6, 0x7f800000
	s_waitcnt lgkmcnt(0)
	v_fmac_f32_e32 v9, v2, v0
	v_max_f32_e32 v0, v3, v1
	v_max_f32_e32 v1, v5, v4
	ds_swizzle_b32 v2, v8 offset:swizzle(SWAP,2)
	ds_swizzle_b32 v3, v9 offset:swizzle(SWAP,2)
	ds_swizzle_b32 v4, v0 offset:swizzle(SWAP,2)
	ds_swizzle_b32 v5, v1 offset:swizzle(SWAP,2)
	s_waitcnt lgkmcnt(3)
	v_add_f32_e32 v2, v8, v2
	s_waitcnt lgkmcnt(2)
	v_add_f32_e32 v3, v9, v3
	s_waitcnt lgkmcnt(1)
	v_max_f32_e32 v4, v4, v4
	s_waitcnt lgkmcnt(0)
	v_max_f32_e32 v5, v5, v5
	ds_swizzle_b32 v7, v2 offset:swizzle(SWAP,4)
	ds_swizzle_b32 v8, v3 offset:swizzle(SWAP,4)
	v_max_f32_e32 v0, v0, v4
	v_max_f32_e32 v1, v1, v5
	ds_swizzle_b32 v4, v0 offset:swizzle(SWAP,4)
	ds_swizzle_b32 v5, v1 offset:swizzle(SWAP,4)
	s_waitcnt lgkmcnt(3)
	v_add_f32_e32 v2, v2, v7
	s_waitcnt lgkmcnt(2)
	v_add_f32_e32 v3, v3, v8
	ds_swizzle_b32 v7, v2 offset:swizzle(SWAP,8)
	ds_swizzle_b32 v8, v3 offset:swizzle(SWAP,8)
	s_waitcnt lgkmcnt(3)
	v_max_f32_e32 v4, v4, v4
	s_waitcnt lgkmcnt(2)
	v_max_f32_e32 v5, v5, v5
	v_max_f32_e32 v0, v0, v4
	v_max_f32_e32 v1, v1, v5
	ds_swizzle_b32 v4, v0 offset:swizzle(SWAP,8)
	ds_swizzle_b32 v5, v1 offset:swizzle(SWAP,8)
	s_waitcnt lgkmcnt(3)
	v_add_f32_e32 v2, v2, v7
	s_waitcnt lgkmcnt(2)
	v_add_f32_e32 v3, v3, v8
	ds_swizzle_b32 v7, v2 offset:swizzle(SWAP,16)
	ds_swizzle_b32 v8, v3 offset:swizzle(SWAP,16)
	s_waitcnt lgkmcnt(3)
	v_max_f32_e32 v4, v4, v4
	s_waitcnt lgkmcnt(2)
	v_max_f32_e32 v5, v5, v5
	v_max_f32_e32 v0, v0, v4
	v_max_f32_e32 v1, v1, v5
	ds_swizzle_b32 v4, v0 offset:swizzle(SWAP,16)
	ds_swizzle_b32 v5, v1 offset:swizzle(SWAP,16)
	s_waitcnt lgkmcnt(3)
	v_add_f32_e32 v2, v2, v7
	s_waitcnt lgkmcnt(2)
	v_add_f32_e32 v3, v3, v8
	v_mov_b32_e32 v7, v2
	v_mov_b32_e32 v8, v3
	s_nop 0
	v_permlane32_swap_b32_e32 v2, v7
	v_permlane32_swap_b32_e32 v3, v8
	v_add_f32_e32 v2, v2, v7
	v_add_f32_e32 v3, v3, v8
	s_waitcnt lgkmcnt(1)
	v_max_f32_e32 v4, v4, v4
	s_waitcnt lgkmcnt(0)
; __global__ void __launch_bounds__(512, 2) fwd_megakernel(Args a) {
;     ...
;         const float negM_a = UNIFORM_F(-8.f * absmax_vec(a.in[6], 64, lane) * absmax_vec(a.in[7], 64, lane) * L2E);
;         const float lam = UNIFORM_F(expf(wave_sum(a.in[8][lane] * a.in[9][lane])) - expf(wave_sum(a.in[10][lane] * a.in[11][lane])) + 0.2f);
;         *(LAS float*)(lds + (LDS_BYTES - 64 + 32)) = lam;
;         for (int rr = 0; rr < (512 + G - 1) / G; ++rr) {
;             int b, h, qblk;
;             if (G == 256) {
;                 const int j = bid >> 3, i = j >> 1; b = bid & 7;
;                 if ((j & 1) == 0) { h = (rr == 0) ? 1 : 0; qblk = i; }
;                 else { h = 2 + rr; qblk = i; }
;             } else { const int u = rr * G + bid; if (u >= 512) break; b = u >> 6; h = (u >> 4) & 3; qblk = u & 15; }
;             const int ta_ = pg8::lane_id_fresh();
;             const int qpos = qblk * 128 + (wave >> 1) * 32 + (ta_ & 31);
;             bf16* qrow = R + ((size_t)b * SEQ + qblk * 128 + (wave >> 1) * 32) * LDQ + C_AQ + h * 128;
;             const bf16* Kg = R + (size_t)b * SEQ * LDQ + C_AK + h * 128; const bf16* Vg = R + (size_t)b * SEQ * LDQ + C_AV + h * 128;
;             const float nslope = -__builtin_amdgcn_exp2f(-2.f * (float)(h + 1)) * L2E;
;             attn_shared_unit<2>((LAS char*)lds, qrow, Kg, Vg, LDQ, SEQ / 64, qpos, qblk * 128 + (wave >> 1) * 32, nslope, negM_a, lam, a.in[12], wave);
;         }
;         const int lnc_ = pg8::lane_id_fresh();
;         const float negM_c = UNIFORM_F(-11.313708499f * absmax_vec(a.in[17], 128, lnc_) * absmax_vec(a.in[18], 128, lnc_) * L2E);
;         for (int u = bid; u < 256; u += G) {
;             const int b = u >> 5, h = (u >> 3) & 3, qblk = u & 7;
;             const int tc_ = pg8::lane_id_fresh();
;             const int qpos = qblk * 256 + wave * 32 + (tc_ & 31);
;             bf16* qrow = R + ((size_t)b * SEQ + qblk * 256 + wave * 32) * LDQ + C_CQ + h * 128;
;             const bf16* Kg = CKV + (size_t)b * NMEM * D + h * 128; const bf16* Vg = Kg + 512;
;             attn_shared_unit<1>((LAS char*)lds, qrow, Kg, Vg, D, NMEM / 64, qpos, 0, 0.f, negM_c, 0.f, a.in[12], wave);
;         }
;         __syncthreads();
;         { const int lnb_ = pg8::lane_id_fresh();
;           const float negM_b = UNIFORM_F(-11.313708499f * absmax_vec(a.in[13], 128, lnb_) * absmax_vec(a.in[14], 128, lnb_) * L2E);
	v_max_f32_e32 v5, v5, v5
	v_mul_f32_e32 v7, 0x3fb8aa3b, v2
	v_mul_f32_e32 v8, 0x3fb8aa3b, v3
	v_max_f32_e32 v0, v0, v4
	v_max_f32_e32 v1, v1, v5
	v_fma_f32 v4, v2, s4, -v7
	v_rndne_f32_e32 v5, v7
	v_fma_f32 v9, v3, s4, -v8
	v_rndne_f32_e32 v10, v8
	v_mov_b32_e32 v11, v0
	v_fmac_f32_e32 v4, 0x32a5705f, v2
	v_sub_f32_e32 v7, v7, v5
	v_mov_b32_e32 v12, v1
	v_fmac_f32_e32 v9, 0x32a5705f, v3
	v_sub_f32_e32 v8, v8, v10
	v_permlane32_swap_b32_e32 v0, v11
	v_add_f32_e32 v4, v7, v4
	v_cvt_i32_f32_e32 v5, v5
	v_permlane32_swap_b32_e32 v1, v12
	v_add_f32_e32 v7, v8, v9
	v_max_f32_e32 v8, v11, v11
	v_max_f32_e32 v0, v0, v0
	v_exp_f32_e32 v4, v4
	v_cvt_i32_f32_e32 v10, v10
	v_max_f32_e32 v9, v12, v12
	v_max_f32_e32 v1, v1, v1
	v_exp_f32_e32 v7, v7
	v_max_f32_e32 v0, v0, v8
	v_max_f32_e32 v1, v1, v9
	v_mul_f32_e32 v0, 0xc1000000, v0
	v_mul_f32_e32 v0, v0, v1
	v_cmp_ngt_f32_e32 vcc, s5, v2
	v_readfirstlane_b32 s4, v0
	v_ldexp_f32 v0, v4, v5
	v_ldexp_f32 v1, v7, v10
	v_cndmask_b32_e32 v0, 0, v0, vcc
	v_cmp_ngt_f32_e32 vcc, s5, v3
	s_nop 1
	v_cndmask_b32_e32 v1, 0, v1, vcc
	v_cmp_nlt_f32_e32 vcc, s6, v2
	v_mov_b32_e32 v2, s33
	s_nop 0
	v_cndmask_b32_e32 v0, v6, v0, vcc
	v_cmp_nlt_f32_e32 vcc, s6, v3
	s_nop 1
	v_cndmask_b32_e32 v1, v6, v1, vcc
	v_sub_f32_e32 v0, v0, v1
	v_cvt_f32_u32_e32 v1, s30
	v_readfirstlane_b32 s5, v0
	v_mov_b32_e32 v0, 0x3e4ccccd
	v_rcp_iflag_f32_e32 v1, v1
	v_add_f32_e32 v0, s5, v0
	s_add_i32 s5, s24, 0x1ff
	s_ashr_i32 s6, s5, 31
	v_mul_f32_e32 v1, 0x4f7ffffe, v1
	v_cvt_u32_f32_e32 v1, v1
	s_abs_i32 s5, s5
	s_xor_b32 s6, s6, s81
	ds_write_b32 v2, v0
	s_waitcnt vmcnt(0)
	v_max_f32_e64 v240, |v240|, |v241|
	v_max_f32_e64 v241, |v243|, |v242|
	v_max_f32_e64 v242, |v244|, |v245|
	v_max_f32_e64 v243, |v247|, |v246|
	ds_swizzle_b32 v244, v240 offset:swizzle(SWAP,1)
	ds_swizzle_b32 v245, v241 offset:swizzle(SWAP,1)
	ds_swizzle_b32 v246, v242 offset:swizzle(SWAP,1)
	ds_swizzle_b32 v247, v243 offset:swizzle(SWAP,1)
	s_waitcnt lgkmcnt(0)
	v_max_f32_e32 v240, v240, v244
	v_max_f32_e32 v241, v241, v245
	v_max_f32_e32 v242, v242, v246
	v_max_f32_e32 v243, v243, v247
	ds_swizzle_b32 v244, v240 offset:swizzle(SWAP,2)
	ds_swizzle_b32 v245, v241 offset:swizzle(SWAP,2)
	ds_swizzle_b32 v246, v242 offset:swizzle(SWAP,2)
	ds_swizzle_b32 v247, v243 offset:swizzle(SWAP,2)
	s_waitcnt lgkmcnt(0)
	v_max_f32_e32 v240, v240, v244
	v_max_f32_e32 v241, v241, v245
	v_max_f32_e32 v242, v242, v246
	v_max_f32_e32 v243, v243, v247
	ds_swizzle_b32 v244, v240 offset:swizzle(SWAP,4)
	ds_swizzle_b32 v245, v241 offset:swizzle(SWAP,4)
	ds_swizzle_b32 v246, v242 offset:swizzle(SWAP,4)
	ds_swizzle_b32 v247, v243 offset:swizzle(SWAP,4)
	s_waitcnt lgkmcnt(0)
	v_max_f32_e32 v240, v240, v244
	v_max_f32_e32 v241, v241, v245
	v_max_f32_e32 v242, v242, v246
	v_max_f32_e32 v243, v243, v247
	ds_swizzle_b32 v244, v240 offset:swizzle(SWAP,8)
	ds_swizzle_b32 v245, v241 offset:swizzle(SWAP,8)
	ds_swizzle_b32 v246, v242 offset:swizzle(SWAP,8)
	ds_swizzle_b32 v247, v243 offset:swizzle(SWAP,8)
	s_waitcnt lgkmcnt(0)
	v_max_f32_e32 v240, v240, v244
	v_max_f32_e32 v241, v241, v245
	v_max_f32_e32 v242, v242, v246
	v_max_f32_e32 v243, v243, v247
	ds_swizzle_b32 v244, v240 offset:swizzle(SWAP,16)
	ds_swizzle_b32 v245, v241 offset:swizzle(SWAP,16)
	ds_swizzle_b32 v246, v242 offset:swizzle(SWAP,16)
	ds_swizzle_b32 v247, v243 offset:swizzle(SWAP,16)
	s_waitcnt lgkmcnt(0)
	v_max_f32_e32 v240, v240, v244
	v_max_f32_e32 v241, v241, v245
	v_max_f32_e32 v242, v242, v246
	v_max_f32_e32 v243, v243, v247
	v_mov_b32_e32 v244, v240
	v_mov_b32_e32 v245, v241
	v_mov_b32_e32 v246, v242
	v_mov_b32_e32 v247, v243
	s_nop 1
	v_permlane32_swap_b32_e32 v240, v244
	v_permlane32_swap_b32_e32 v241, v245
	v_permlane32_swap_b32_e32 v242, v246
	v_permlane32_swap_b32_e32 v243, v247
	v_max_f32_e32 v240, v240, v244
	v_max_f32_e32 v241, v241, v245
	v_max_f32_e32 v242, v242, v246
	v_max_f32_e32 v243, v243, v247
	v_mul_f32_e32 v240, 0xc13504f3, v240
	v_mul_f32_e32 v242, 0xc13504f3, v242
	v_mul_f32_e32 v240, v240, v241
	v_mul_f32_e32 v242, v242, v243
	s_nop 0
	v_readfirstlane_b32 s98, v240
	v_readfirstlane_b32 s99, v242
	v_readfirstlane_b32 s31, v1
	s_mul_i32 s8, s8, s31
	s_mul_hi_u32 s8, s31, s8
	s_add_i32 s31, s31, s8
	s_mul_hi_u32 s8, s5, s31
	s_mul_i32 s9, s8, s30
	s_sub_i32 s5, s5, s9
	s_add_i32 s9, s8, 1
	s_sub_i32 s10, s5, s30
	s_cmp_ge_u32 s5, s30
	s_cselect_b32 s8, s9, s8
	s_cselect_b32 s5, s10, s5
	s_add_i32 s9, s8, 1
	s_cmp_ge_u32 s5, s30
	s_cselect_b32 s5, s9, s8
	s_xor_b32 s5, s5, s6
	s_sub_i32 s62, s5, s6
	s_cmp_lt_i32 s62, 1
	s_cbranch_scc1 .LBB0_293
	s_ashr_i32 s63, s2, 4
	s_and_b32 s64, s2, 7
	v_mov_b32_e32 v0, 0x3fb8aa3b
	s_bitcmp0_b32 s2, 3
	v_mul_f32_e32 v254, s4, v0
	s_cselect_b64 s[8:9], -1, 0
	s_lshr_b32 s4, s39, 2
	s_and_b32 s65, s4, 0x3fffffe0
	s_bfe_u32 s4, s39, 0x10006
	s_lshl_b32 s6, s4, 7
	s_add_i32 s66, s6, 0
	s_lshl_b32 s6, s96, 13
	s_and_b32 s6, s6, 0x7fffc000
	s_lshl_b32 s5, s4, 6
	s_add_i32 s67, s6, 0
	s_and_b32 s6, 64, s39
	s_cmp_eq_u32 s4, 0
	s_cselect_b64 s[10:11], -1, 0
	s_cmp_lg_u32 s6, 0
	s_cselect_b64 s[20:21], -1, 0
	s_add_u32 s68, s14, 0x31b0810
	s_mov_b32 s22, 2.0
	s_mov_b32 s44, 0x41000000
	s_mov_b32 s46, 0x41200000
	s_mov_b32 s48, 0x41800000
	s_mov_b32 s50, 0x41900000
	s_mov_b32 s52, 0x41c00000
	s_mov_b32 s54, 0x41d00000
	s_addc_u32 s69, s15, 0
	s_movk_i32 s70, 0x3400
	v_mov_b32_e32 v209, 0
	s_lshl_b32 s6, s5, 1
	s_mov_b32 s71, 0x43180000
	s_movk_i32 s72, 0x110
	s_add_i32 s73, 0, 0x10000
	s_mov_b32 s23, 0x40400000
	s_mov_b32 s45, 0x41100000
	s_mov_b32 s47, 0x41300000
	s_mov_b32 s49, 0x41880000
	s_mov_b32 s51, 0x41980000
	s_mov_b32 s53, 0x41c80000
	s_mov_b32 s55, 0x41d80000
	v_mov_b32_e32 v138, 0xd0000
	s_mov_b32 s76, s7
	s_branch .LBB0_263

; __device__ __forceinline__ int lane_id_fresh() { int z = 0; asm volatile("" : "+s"(z)); return __builtin_amdgcn_mbcnt_hi(~0u, __builtin_amdgcn_mbcnt_lo(~0u, z)); }
; #define LAS __attribute__((address_space(3)))
; #define UNIFORM_F(v) __builtin_bit_cast(float, __builtin_amdgcn_readfirstlane(__builtin_bit_cast(int, (float)(v))))
; __global__ void __launch_bounds__(512, 2) fwd_megakernel(Args a) {
;     ...
;         const int lnc_ = pg8::lane_id_fresh();
;         const float negM_c = UNIFORM_F(-11.313708499f * absmax_vec(a.in[17], 128, lnc_) * absmax_vec(a.in[18], 128, lnc_) * L2E);
;         for (int u = bid; u < 256; u += G) {
;             const int b = u >> 5, h = (u >> 3) & 3, qblk = u & 7;
;             const int tc_ = pg8::lane_id_fresh();
;             const int qpos = qblk * 256 + wave * 32 + (tc_ & 31);
;             bf16* qrow = R + ((size_t)b * SEQ + qblk * 256 + wave * 32) * LDQ + C_CQ + h * 128;
;             const bf16* Kg = CKV + (size_t)b * NMEM * D + h * 128; const bf16* Vg = Kg + 512;
;             attn_shared_unit<1>((LAS char*)lds, qrow, Kg, Vg, D, NMEM / 64, qpos, 0, 0.f, negM_c, 0.f, a.in[12], wave);
.LBB0_293:
	s_cmpk_lt_i32 s2, 0x100
	s_cselect_b64 s[84:85], -1, 0
	s_cmpk_gt_i32 s2, 0xff
	s_mov_b32 s4, s98
	s_cbranch_scc1 .LBB0_302
	v_mov_b32_e32 v0, 0x3fb8aa3b
	s_lshl_b32 s6, s96, 5
	v_mul_f32_e32 v0, s4, v0
	s_add_u32 s4, s12, 0x2420400
	v_mov_b32_e32 v1, v0
	v_mov_b32_e32 v2, v0
	v_mov_b32_e32 v3, v0
	v_mov_b32_e32 v4, v0
	v_mov_b32_e32 v5, v0
	v_mov_b32_e32 v6, v0
	v_mov_b32_e32 v7, v0
	v_mov_b32_e32 v8, v0
	v_mov_b32_e32 v9, v0
	v_mov_b32_e32 v10, v0
	v_mov_b32_e32 v11, v0
	v_mov_b32_e32 v12, v0
	v_mov_b32_e32 v13, v0
	v_mov_b32_e32 v14, v0
	v_mov_b32_e32 v15, v0
	s_addc_u32 s5, s13, 0
	s_lshl_b32 s7, s2, 4
	s_lshl_b32 s22, s24, 4
	s_movk_i32 s23, 0x3400
	v_mov_b32_e32 v161, 0
	s_movk_i32 s26, 0x110
	s_movk_i32 s27, 0x140
	s_mov_b64 s[8:9], 0x20000
	s_mov_b32 s33, s2

; __device__ __forceinline__ int lane_id_fresh() { int z = 0; asm volatile("" : "+s"(z)); return __builtin_amdgcn_mbcnt_hi(~0u, __builtin_amdgcn_mbcnt_lo(~0u, z)); }
; #define UNIFORM_F(v) __builtin_bit_cast(float, __builtin_amdgcn_readfirstlane(__builtin_bit_cast(int, (float)(v))))
; __global__ void __launch_bounds__(512, 2) fwd_megakernel(Args a) {
;     ...
;         __syncthreads();
;         { const int lnb_ = pg8::lane_id_fresh();
;           const float negM_b = UNIFORM_F(-11.313708499f * absmax_vec(a.in[13], 128, lnb_) * absmax_vec(a.in[14], 128, lnb_) * L2E);
;           const int jb = bid >> 3, heavy = jb & 1, xq = bid & 7, ib = jb >> 1;
;           const int nbu = (G == 256) ? (heavy ? 2 : 4) : (768 + G - 1) / G;
;           for (int rr = 0; rr < nbu; ++rr) {
.LBB0_302:
	s_mov_b32 s8, 0
	s_waitcnt lgkmcnt(0)
	s_barrier
	s_and_b64 vcc, exec, s[42:43]
	s_mov_b32 s6, s99
	s_cbranch_vccz .LBB0_304
	s_add_i32 s4, s24, 0x2ff
	s_ashr_i32 s5, s4, 31
	s_abs_i32 s4, s4
	s_mul_hi_u32 s7, s4, s31
	s_mul_i32 s8, s7, s30
	s_sub_i32 s4, s4, s8
	s_xor_b32 s5, s5, s81
	s_add_i32 s8, s7, 1
	s_sub_i32 s9, s4, s30
	s_cmp_ge_u32 s4, s30
	s_cselect_b32 s7, s8, s7
	s_cselect_b32 s4, s9, s4
	s_add_i32 s8, s7, 1
	s_cmp_ge_u32 s4, s30
	s_cselect_b32 s4, s8, s7
	s_xor_b32 s4, s4, s5
	s_sub_i32 s70, s4, s5
	s_mov_b64 s[4:5], 0
	s_branch .LBB0_305
